# PRE: S0 store-drain waits removed, team 0 instead sleeps 1536 cycles at the head of each item (controlled stagger)
# baseline (speedup 1.0000x reference)
.LBB0_81:
	s_bitcmp1_b32 s60, 0
	s_cbranch_scc1 .Lstg_1
	s_sleep 24
